# readout and rwkv_prep loop 2: per-token global loads prefetched two tokens ahead into alternating register sets
# speedup vs baseline: 1.0029x; 1.0029x over previous
.LBB0_707:
	v_mov_b32_e32 v94, s2
	s_waitcnt lgkmcnt(12)
	v_pk_mul_f32 v[90:91], v[136:137], v[6:7]
	v_pk_fma_f32 v[90:91], v[138:139], v[8:9], v[90:91]
	ds_read_b128 v[136:139], v94 offset:512
	v_pk_mul_f32 v[92:93], v[140:141], v[56:57]
	v_pk_fma_f32 v[92:93], v[142:143], v[58:59], v[92:93]
	ds_read_b128 v[140:143], v94 offset:640
	v_pk_fma_f32 v[90:91], v[144:145], v[10:11], v[90:91]
	v_pk_fma_f32 v[90:91], v[146:147], v[12:13], v[90:91]
	ds_read_b128 v[144:147], v94 offset:528
	v_pk_fma_f32 v[92:93], v[148:149], v[60:61], v[92:93]
	v_pk_fma_f32 v[92:93], v[150:151], v[62:63], v[92:93]
	ds_read_b128 v[148:151], v94 offset:656
	s_waitcnt lgkmcnt(12)
	v_pk_fma_f32 v[90:91], v[152:153], v[14:15], v[90:91]
	v_pk_fma_f32 v[90:91], v[154:155], v[16:17], v[90:91]
	ds_read_b128 v[152:155], v94 offset:544
	v_pk_fma_f32 v[92:93], v[156:157], v[64:65], v[92:93]
	v_pk_fma_f32 v[92:93], v[158:159], v[66:67], v[92:93]
	ds_read_b128 v[156:159], v94 offset:672
	v_pk_fma_f32 v[90:91], v[160:161], v[18:19], v[90:91]
	v_pk_fma_f32 v[90:91], v[162:163], v[20:21], v[90:91]
	ds_read_b128 v[160:163], v94 offset:560
	v_pk_fma_f32 v[92:93], v[164:165], v[68:69], v[92:93]
	v_pk_fma_f32 v[92:93], v[166:167], v[70:71], v[92:93]
	ds_read_b128 v[164:167], v94 offset:688
	s_waitcnt lgkmcnt(12)
	v_pk_fma_f32 v[90:91], v[184:185], v[22:23], v[90:91]
	v_pk_fma_f32 v[90:91], v[186:187], v[24:25], v[90:91]
	ds_read_b128 v[184:187], v94 offset:576
	v_pk_fma_f32 v[92:93], v[188:189], v[72:73], v[92:93]
	v_pk_fma_f32 v[92:93], v[190:191], v[74:75], v[92:93]
	ds_read_b128 v[188:191], v94 offset:704
	v_pk_fma_f32 v[90:91], v[192:193], v[26:27], v[90:91]
	v_pk_fma_f32 v[90:91], v[194:195], v[28:29], v[90:91]
	ds_read_b128 v[192:195], v94 offset:592
	v_pk_fma_f32 v[92:93], v[196:197], v[76:77], v[92:93]
	v_pk_fma_f32 v[92:93], v[198:199], v[78:79], v[92:93]
	ds_read_b128 v[196:199], v94 offset:720
	s_waitcnt lgkmcnt(12)
	v_pk_fma_f32 v[90:91], v[200:201], v[30:31], v[90:91]
	v_pk_fma_f32 v[90:91], v[202:203], v[32:33], v[90:91]
	ds_read_b128 v[200:203], v94 offset:608
	v_pk_fma_f32 v[92:93], v[212:213], v[80:81], v[92:93]
	v_pk_fma_f32 v[92:93], v[214:215], v[82:83], v[92:93]
	ds_read_b128 v[212:215], v94 offset:736
	v_pk_fma_f32 v[90:91], v[216:217], v[34:35], v[90:91]
	v_pk_fma_f32 v[90:91], v[218:219], v[36:37], v[90:91]
	ds_read_b128 v[216:219], v94 offset:624
	v_pk_fma_f32 v[92:93], v[220:221], v[84:85], v[92:93]
	v_pk_fma_f32 v[92:93], v[222:223], v[86:87], v[92:93]
	ds_read_b128 v[220:223], v94 offset:752
	s_addk_i32 s2, 0x200
	v_add_f32_e32 v98, v90, v88
	v_add_f32_e32 v99, v92, v89
	v_add_f32_e32 v98, v98, v91
	v_add_f32_e32 v99, v99, v93
	v_mul_f32_e32 v98, 0xbfb8aa3b, v98
	v_mul_f32_e32 v99, 0xbfb8aa3b, v99
	v_exp_f32_e32 v98, v98
	v_exp_f32_e32 v99, v99
	s_nop 0
	v_add_f32_e32 v98, 1.0, v98
	v_add_f32_e32 v99, 1.0, v99
	v_rcp_f32_e32 v98, v98
	v_rcp_f32_e32 v99, v99
	s_nop 0
	v_mul_f32_e32 v98, 0xbf60028a, v98
	v_mul_f32_e32 v99, 0xbf60028a, v99
	v_exp_f32_e32 v98, v98
	v_exp_f32_e32 v99, v99
	s_cmpk_eq_i32 s2, 0x4400
	s_nop 0
	global_store_dword v95, v98, s[14:15]
	global_store_dword v95, v99, s[16:17]
	v_add_u32_e32 v95, 0x400, v95
	s_cbranch_scc0 .LBB0_707
	s_waitcnt lgkmcnt(0)
	v_lshlrev_b64 v[6:7], 2, v[2:3]
	v_lshl_add_u64 v[66:67], s[68:69], 0, v[6:7]
	v_mov_b32_e32 v96, v6
	global_load_dword v8, v96, s[68:69]
	global_load_dword v9, v96, s[68:69] offset:1024
	global_load_dword v10, v96, s[68:69] offset:2048
	global_load_dword v11, v96, s[68:69] offset:3072
	v_add_u32_e32 v96, 0x1000, v96
	global_load_dword v12, v96, s[68:69]
	global_load_dword v13, v96, s[68:69] offset:1024
	global_load_dword v14, v96, s[68:69] offset:2048
	global_load_dword v15, v96, s[68:69] offset:3072
	v_add_u32_e32 v96, 0x1000, v96
	global_load_dword v16, v96, s[68:69]
	global_load_dword v17, v96, s[68:69] offset:1024
	global_load_dword v18, v96, s[68:69] offset:2048
	global_load_dword v19, v96, s[68:69] offset:3072
	v_add_u32_e32 v96, 0x1000, v96
	global_load_dword v20, v96, s[68:69]
	global_load_dword v21, v96, s[68:69] offset:1024
	global_load_dword v22, v96, s[68:69] offset:2048
	global_load_dword v23, v96, s[68:69] offset:3072
	v_add_u32_e32 v96, 0x1000, v96
	global_load_dword v24, v96, s[68:69]
	global_load_dword v25, v96, s[68:69] offset:1024
	global_load_dword v26, v96, s[68:69] offset:2048
	global_load_dword v27, v96, s[68:69] offset:3072
	v_add_u32_e32 v96, 0x1000, v96
	global_load_dword v28, v96, s[68:69]
	global_load_dword v29, v96, s[68:69] offset:1024
	global_load_dword v30, v96, s[68:69] offset:2048
	global_load_dword v31, v96, s[68:69] offset:3072
	v_add_u32_e32 v96, 0x1000, v96
	global_load_dword v32, v96, s[68:69]
	global_load_dword v33, v96, s[68:69] offset:1024
	global_load_dword v34, v96, s[68:69] offset:2048
	global_load_dword v35, v96, s[68:69] offset:3072
	v_add_u32_e32 v96, 0x1000, v96
	global_load_dword v36, v96, s[68:69]
	global_load_dword v37, v96, s[68:69] offset:1024
	global_load_dword v38, v96, s[68:69] offset:2048
	global_load_dword v39, v96, s[68:69] offset:3072
	v_add_u32_e32 v96, 0x1000, v96
	global_load_dword v56, v96, s[68:69]
	global_load_dword v57, v96, s[68:69] offset:1024
	global_load_dword v58, v96, s[68:69] offset:2048
	global_load_dword v59, v96, s[68:69] offset:3072
	v_add_u32_e32 v96, 0x1000, v96
	global_load_dword v60, v96, s[68:69]
	global_load_dword v61, v96, s[68:69] offset:1024
	global_load_dword v62, v96, s[68:69] offset:2048
	global_load_dword v63, v96, s[68:69] offset:3072
	v_add_u32_e32 v96, 0x1000, v96
	global_load_dword v64, v96, s[68:69]
	global_load_dword v65, v96, s[68:69] offset:1024
	global_load_dword v66, v96, s[68:69] offset:2048
	global_load_dword v67, v96, s[68:69] offset:3072
	v_add_u32_e32 v96, 0x1000, v96
	global_load_dword v68, v96, s[68:69]
	global_load_dword v69, v96, s[68:69] offset:1024
	global_load_dword v70, v96, s[68:69] offset:2048
	global_load_dword v71, v96, s[68:69] offset:3072
	v_add_u32_e32 v96, 0x1000, v96
	global_load_dword v72, v96, s[68:69]
	global_load_dword v73, v96, s[68:69] offset:1024
	global_load_dword v74, v96, s[68:69] offset:2048
	global_load_dword v75, v96, s[68:69] offset:3072
	v_add_u32_e32 v96, 0x1000, v96
	global_load_dword v76, v96, s[68:69]
	global_load_dword v77, v96, s[68:69] offset:1024
	global_load_dword v78, v96, s[68:69] offset:2048
	global_load_dword v79, v96, s[68:69] offset:3072
	v_add_u32_e32 v96, 0x1000, v96
	global_load_dword v80, v96, s[68:69]
	global_load_dword v81, v96, s[68:69] offset:1024
	global_load_dword v82, v96, s[68:69] offset:2048
	global_load_dword v83, v96, s[68:69] offset:3072
	v_add_u32_e32 v96, 0x1000, v96
	global_load_dword v84, v96, s[68:69]
	global_load_dword v85, v96, s[68:69] offset:1024
	global_load_dword v86, v96, s[68:69] offset:2048
	global_load_dword v87, v96, s[68:69] offset:3072
	s_mov_b32 s0, 0xc000
	v_readlane_b32 s44, v210, 18
	s_nop 0
	s_nop 0
	s_nop 0
	v_readlane_b32 s52, v210, 26
	s_nop 0
	s_nop 0
	s_nop 0
	v_readlane_b32 s53, v210, 27
	s_nop 0
	s_nop 0
	s_nop 0
	v_lshl_add_u64 v[4:5], v[4:5], 2, s[52:53]
	s_nop 0
	s_nop 0
	s_nop 0
	s_movk_i32 s0, 0x5000
	s_nop 0
	s_mov_b32 s0, 0xd000
	s_nop 0
	s_movk_i32 s0, 0x6000
	s_nop 0
	s_mov_b32 s0, 0xe000
	s_nop 0
	s_movk_i32 s0, 0x7000
	s_nop 0
	s_mov_b32 s0, 0xf000
	s_nop 0
	s_nop 0
	s_nop 0
	s_nop 0
	s_nop 0
	s_nop 0
	s_nop 0
	s_nop 0
	s_nop 0
	s_nop 0
	s_nop 0
	s_nop 0
	global_load_dword v88, v[4:5], off
	global_load_dword v89, v[4:5], off offset:1024
	v_and_b32_e32 v5, 63, v2
	v_ashrrev_i32_e32 v4, 6, v2
	v_readlane_b32 s56, v210, 30
	v_readlane_b32 s57, v210, 31
	v_readlane_b32 s58, v210, 32
	v_readlane_b32 s59, v210, 33
	v_cmp_eq_u32_e32 vcc, 0, v5
	v_ashrrev_i32_e32 v5, 31, v4
	v_readlane_b32 s80, v208, 27
	s_movk_i32 s61, 0x4000
	s_mov_b32 s6, 0
	v_lshl_add_u64 v[4:5], v[4:5], 2, s[24:25]
	v_lshl_add_u64 v[6:7], s[12:13], 0, v[6:7]
	s_movk_i32 s7, 0x100
	v_readlane_b32 s81, v208, 28
	v_readlane_b32 s82, v208, 29
	v_readlane_b32 s83, v208, 30
	v_readlane_b32 s84, v208, 31
	v_readlane_b32 s85, v208, 32
	v_readlane_b32 s86, v208, 33
	v_readlane_b32 s87, v208, 34
	v_readlane_b32 s88, v208, 35
	v_readlane_b32 s89, v208, 36
	v_readlane_b32 s90, v208, 37
	v_readlane_b32 s91, v208, 38
	v_readlane_b32 s92, v208, 39
	v_readlane_b32 s93, v208, 40
	v_readlane_b32 s94, v208, 41
	v_readlane_b32 s95, v208, 42
	s_mov_b32 s56, 0x10000
	s_mov_b32 s57, 0x20000
	s_mov_b32 s58, 0x30000
	s_movk_i32 s59, 0x70
	v_readlane_b32 s45, v210, 19
	v_readlane_b32 s46, v210, 20
	v_readlane_b32 s47, v210, 21
	v_readlane_b32 s48, v210, 22
	v_readlane_b32 s49, v210, 23
	v_readlane_b32 s50, v210, 24
	v_readlane_b32 s51, v210, 25
	v_readlane_b32 s54, v210, 28
	v_readlane_b32 s55, v210, 29
	s_waitcnt vmcnt(0) lgkmcnt(0)
	v_mov_b32_e32 v94, s7
	ds_read_b128 v[136:139], v94 offset:0
	ds_read_b128 v[140:143], v94 offset:128
	ds_read_b128 v[144:147], v94 offset:16
	ds_read_b128 v[148:151], v94 offset:144
	ds_read_b128 v[152:155], v94 offset:32
	ds_read_b128 v[156:159], v94 offset:160
	ds_read_b128 v[160:163], v94 offset:48
	ds_read_b128 v[164:167], v94 offset:176
	ds_read_b128 v[184:187], v94 offset:64
	ds_read_b128 v[188:191], v94 offset:192
	ds_read_b128 v[192:195], v94 offset:80
	ds_read_b128 v[196:199], v94 offset:208
	ds_read_b128 v[200:203], v94 offset:96
	ds_read_b128 v[212:215], v94 offset:224
	ds_read_b128 v[216:219], v94 offset:112
	ds_read_b128 v[220:223], v94 offset:240
	s_lshl_b32 s4, s97, 10
	v_lshlrev_b32_e32 v95, 2, v2
	v_add_u32_e32 v95, s4, v95
	s_mov_b32 s1, 0
	v_mad_i64_i32 v[44:45], s[2:3], s97, v178, v[6:7]
	global_load_dword v42, v[44:45], off
	global_load_dword v43, v[44:45], off offset:1024
	s_add_i32 s8, s97, 1
	v_mad_i64_i32 v[44:45], s[2:3], s8, v178, v[6:7]
	global_load_dword v48, v[44:45], off
	global_load_dword v49, v[44:45], off offset:1024
	s_waitcnt vmcnt(2)
	s_branch .Lrw2_even_entry
.LBB0_710:
	s_waitcnt vmcnt(6)
.Lrw2_even_entry:
	v_mov_b32_e32 v94, s7
	s_add_i32 s0, s97, s6
	v_mov_b32_e32 v50, v42
	v_mov_b32_e32 v51, v43
	s_add_i32 s8, s0, 2
	v_mul_f32_e32 v97, v0, v51
	v_mad_i64_i32 v[44:45], s[2:3], s8, v178, v[6:7]
	v_mul_f32_e32 v102, v97, v97
	global_load_dword v42, v[44:45], off
	global_load_dword v43, v[44:45], off offset:1024
	s_waitcnt lgkmcnt(12)
	v_pk_mul_f32 v[90:91], v[136:137], v[8:9]
	v_pk_fma_f32 v[90:91], v[138:139], v[10:11], v[90:91]
	ds_read_b128 v[136:139], v94 offset:512
	v_add_f32_dpp v102, v102, v102 quad_perm:[1,0,3,2] row_mask:0xf bank_mask:0xf bound_ctrl:1
	v_pk_mul_f32 v[92:93], v[140:141], v[56:57]
	v_pk_fma_f32 v[92:93], v[142:143], v[58:59], v[92:93]
	ds_read_b128 v[140:143], v94 offset:640
	v_add_f32_dpp v102, v102, v102 quad_perm:[2,3,0,1] row_mask:0xf bank_mask:0xf bound_ctrl:1
	v_pk_fma_f32 v[90:91], v[144:145], v[12:13], v[90:91]
	v_pk_fma_f32 v[90:91], v[146:147], v[14:15], v[90:91]
	ds_read_b128 v[144:147], v94 offset:528
	v_add_f32_dpp v102, v102, v102 row_half_mirror row_mask:0xf bank_mask:0xf bound_ctrl:1
	v_pk_fma_f32 v[92:93], v[148:149], v[60:61], v[92:93]
	v_pk_fma_f32 v[92:93], v[150:151], v[62:63], v[92:93]
	ds_read_b128 v[148:151], v94 offset:656
	v_add_f32_dpp v102, v102, v102 row_mirror row_mask:0xf bank_mask:0xf bound_ctrl:1
	s_waitcnt lgkmcnt(12)
	v_pk_fma_f32 v[90:91], v[152:153], v[16:17], v[90:91]
	v_pk_fma_f32 v[90:91], v[154:155], v[18:19], v[90:91]
	ds_read_b128 v[152:155], v94 offset:544
	v_add_f32_dpp v102, v102, v102 row_bcast:15 row_mask:0xa bank_mask:0xf
	v_pk_fma_f32 v[92:93], v[156:157], v[64:65], v[92:93]
	v_pk_fma_f32 v[92:93], v[158:159], v[66:67], v[92:93]
	ds_read_b128 v[156:159], v94 offset:672
	v_add_f32_dpp v102, v102, v102 row_bcast:31 row_mask:0xc bank_mask:0xf
	v_pk_fma_f32 v[90:91], v[160:161], v[20:21], v[90:91]
	v_pk_fma_f32 v[90:91], v[162:163], v[22:23], v[90:91]
	ds_read_b128 v[160:163], v94 offset:560
	v_pk_fma_f32 v[92:93], v[164:165], v[68:69], v[92:93]
	v_pk_fma_f32 v[92:93], v[166:167], v[70:71], v[92:93]
	ds_read_b128 v[164:167], v94 offset:688
	s_waitcnt lgkmcnt(12)
	v_pk_fma_f32 v[90:91], v[184:185], v[24:25], v[90:91]
	v_pk_fma_f32 v[90:91], v[186:187], v[26:27], v[90:91]
	ds_read_b128 v[184:187], v94 offset:576
	v_readlane_b32 s8, v102, 63
	v_pk_fma_f32 v[92:93], v[188:189], v[72:73], v[92:93]
	v_pk_fma_f32 v[92:93], v[190:191], v[74:75], v[92:93]
	ds_read_b128 v[188:191], v94 offset:704
	v_pk_fma_f32 v[90:91], v[192:193], v[28:29], v[90:91]
	v_pk_fma_f32 v[90:91], v[194:195], v[30:31], v[90:91]
	ds_read_b128 v[192:195], v94 offset:592
	v_pk_fma_f32 v[92:93], v[196:197], v[76:77], v[92:93]
	v_pk_fma_f32 v[92:93], v[198:199], v[78:79], v[92:93]
	ds_read_b128 v[196:199], v94 offset:720
	s_waitcnt lgkmcnt(12)
	v_pk_fma_f32 v[90:91], v[200:201], v[32:33], v[90:91]
	v_pk_fma_f32 v[90:91], v[202:203], v[34:35], v[90:91]
	ds_read_b128 v[200:203], v94 offset:608
	v_pk_fma_f32 v[92:93], v[212:213], v[80:81], v[92:93]
	v_pk_fma_f32 v[92:93], v[214:215], v[82:83], v[92:93]
	ds_read_b128 v[212:215], v94 offset:736
	v_pk_fma_f32 v[90:91], v[216:217], v[36:37], v[90:91]
	v_pk_fma_f32 v[90:91], v[218:219], v[38:39], v[90:91]
	ds_read_b128 v[216:219], v94 offset:624
	v_pk_fma_f32 v[92:93], v[220:221], v[84:85], v[92:93]
	v_pk_fma_f32 v[92:93], v[222:223], v[86:87], v[92:93]
	ds_read_b128 v[220:223], v94 offset:752
	v_add_f32_e32 v98, v90, v88
	v_add_f32_e32 v99, v92, v89
	v_add_f32_e32 v98, v98, v91
	v_add_f32_e32 v99, v99, v93
	v_mul_f32_e32 v98, 0xbfb8aa3b, v98
	v_mul_f32_e32 v99, 0xbfb8aa3b, v99
	v_exp_f32_e32 v98, v98
	v_exp_f32_e32 v99, v99
	v_mov_b32_e32 v103, s8
	v_add_f32_e32 v98, 1.0, v98
	v_add_f32_e32 v99, 1.0, v99
	v_rcp_f32_e32 v98, v98
	v_rcp_f32_e32 v99, v99
	v_max_f32_e32 v103, 0x179abe15, v103
	v_rsq_f32_e32 v103, v103
	v_add_f32_e32 v112, -1.0, v98
	v_add_f32_e32 v113, -1.0, v99
	v_fma_f32 v112, v54, v112, 1.0
	v_fma_f32 v113, v54, v113, 1.0
	v_mul_f32_e32 v112, v51, v112
	v_fmac_f32_e32 v112, v51, v113
	v_mul_f32_e32 v97, v97, v103
	v_mul_f32_e32 v112, v50, v112
	v_mul_f32_e32 v114, v55, v112
	global_store_dword v95, v98, s[18:19]
	global_store_dword v95, v99, s[20:21]
	v_add_f32_dpp v114, v114, v114 quad_perm:[1,0,3,2] row_mask:0xf bank_mask:0xf bound_ctrl:1
	global_store_dword v95, v97, s[22:23]
	s_nop 0
	v_add_f32_dpp v114, v114, v114 quad_perm:[2,3,0,1] row_mask:0xf bank_mask:0xf bound_ctrl:1
	s_nop 1
	v_add_f32_dpp v114, v114, v114 row_half_mirror row_mask:0xf bank_mask:0xf bound_ctrl:1
	v_add_u32_e32 v95, 0x400, v95
	s_addk_i32 s7, 0x200
	v_add_f32_dpp v114, v114, v114 row_mirror row_mask:0xf bank_mask:0xf bound_ctrl:1
	s_nop 1
	v_add_f32_dpp v114, v114, v114 row_bcast:15 row_mask:0xa bank_mask:0xf
	s_nop 1
	v_add_f32_dpp v114, v114, v114 row_bcast:31 row_mask:0xc bank_mask:0xf
	s_nop 1
	v_readlane_b32 s9, v114, 63
	s_and_saveexec_b64 s[4:5], vcc
	v_mov_b32_e32 v103, s9
	v_lshl_add_u64 v[46:47], s[0:1], 4, v[4:5]
	global_store_dword v[46:47], v103, off
	s_or_b64 exec, exec, s[4:5]
	s_add_i32 s6, s6, 1
	s_waitcnt vmcnt(6)
	v_mov_b32_e32 v94, s7
	s_add_i32 s0, s97, s6
	v_mov_b32_e32 v50, v48
	v_mov_b32_e32 v51, v49
	s_add_i32 s8, s0, 2
	v_mul_f32_e32 v97, v0, v51
	v_mad_i64_i32 v[44:45], s[2:3], s8, v178, v[6:7]
	v_mul_f32_e32 v102, v97, v97
	global_load_dword v48, v[44:45], off
	global_load_dword v49, v[44:45], off offset:1024
	s_waitcnt lgkmcnt(12)
	v_pk_mul_f32 v[90:91], v[136:137], v[8:9]
	v_pk_fma_f32 v[90:91], v[138:139], v[10:11], v[90:91]
	ds_read_b128 v[136:139], v94 offset:512
	v_add_f32_dpp v102, v102, v102 quad_perm:[1,0,3,2] row_mask:0xf bank_mask:0xf bound_ctrl:1
	v_pk_mul_f32 v[92:93], v[140:141], v[56:57]
	v_pk_fma_f32 v[92:93], v[142:143], v[58:59], v[92:93]
	ds_read_b128 v[140:143], v94 offset:640
	v_add_f32_dpp v102, v102, v102 quad_perm:[2,3,0,1] row_mask:0xf bank_mask:0xf bound_ctrl:1
	v_pk_fma_f32 v[90:91], v[144:145], v[12:13], v[90:91]
	v_pk_fma_f32 v[90:91], v[146:147], v[14:15], v[90:91]
	ds_read_b128 v[144:147], v94 offset:528
	v_add_f32_dpp v102, v102, v102 row_half_mirror row_mask:0xf bank_mask:0xf bound_ctrl:1
	v_pk_fma_f32 v[92:93], v[148:149], v[60:61], v[92:93]
	v_pk_fma_f32 v[92:93], v[150:151], v[62:63], v[92:93]
	ds_read_b128 v[148:151], v94 offset:656
	v_add_f32_dpp v102, v102, v102 row_mirror row_mask:0xf bank_mask:0xf bound_ctrl:1
	s_waitcnt lgkmcnt(12)
	v_pk_fma_f32 v[90:91], v[152:153], v[16:17], v[90:91]
	v_pk_fma_f32 v[90:91], v[154:155], v[18:19], v[90:91]
	ds_read_b128 v[152:155], v94 offset:544
	v_add_f32_dpp v102, v102, v102 row_bcast:15 row_mask:0xa bank_mask:0xf
	v_pk_fma_f32 v[92:93], v[156:157], v[64:65], v[92:93]
	v_pk_fma_f32 v[92:93], v[158:159], v[66:67], v[92:93]
	ds_read_b128 v[156:159], v94 offset:672
	v_add_f32_dpp v102, v102, v102 row_bcast:31 row_mask:0xc bank_mask:0xf
	v_pk_fma_f32 v[90:91], v[160:161], v[20:21], v[90:91]
	v_pk_fma_f32 v[90:91], v[162:163], v[22:23], v[90:91]
	ds_read_b128 v[160:163], v94 offset:560
	v_pk_fma_f32 v[92:93], v[164:165], v[68:69], v[92:93]
	v_pk_fma_f32 v[92:93], v[166:167], v[70:71], v[92:93]
	ds_read_b128 v[164:167], v94 offset:688
	s_waitcnt lgkmcnt(12)
	v_pk_fma_f32 v[90:91], v[184:185], v[24:25], v[90:91]
	v_pk_fma_f32 v[90:91], v[186:187], v[26:27], v[90:91]
	ds_read_b128 v[184:187], v94 offset:576
	v_readlane_b32 s8, v102, 63
	v_pk_fma_f32 v[92:93], v[188:189], v[72:73], v[92:93]
	v_pk_fma_f32 v[92:93], v[190:191], v[74:75], v[92:93]
	ds_read_b128 v[188:191], v94 offset:704
	v_pk_fma_f32 v[90:91], v[192:193], v[28:29], v[90:91]
	v_pk_fma_f32 v[90:91], v[194:195], v[30:31], v[90:91]
	ds_read_b128 v[192:195], v94 offset:592
	v_pk_fma_f32 v[92:93], v[196:197], v[76:77], v[92:93]
	v_pk_fma_f32 v[92:93], v[198:199], v[78:79], v[92:93]
	ds_read_b128 v[196:199], v94 offset:720
	s_waitcnt lgkmcnt(12)
	v_pk_fma_f32 v[90:91], v[200:201], v[32:33], v[90:91]
	v_pk_fma_f32 v[90:91], v[202:203], v[34:35], v[90:91]
	ds_read_b128 v[200:203], v94 offset:608
	v_pk_fma_f32 v[92:93], v[212:213], v[80:81], v[92:93]
	v_pk_fma_f32 v[92:93], v[214:215], v[82:83], v[92:93]
	ds_read_b128 v[212:215], v94 offset:736
	v_pk_fma_f32 v[90:91], v[216:217], v[36:37], v[90:91]
	v_pk_fma_f32 v[90:91], v[218:219], v[38:39], v[90:91]
	ds_read_b128 v[216:219], v94 offset:624
	v_pk_fma_f32 v[92:93], v[220:221], v[84:85], v[92:93]
	v_pk_fma_f32 v[92:93], v[222:223], v[86:87], v[92:93]
	ds_read_b128 v[220:223], v94 offset:752
	v_add_f32_e32 v98, v90, v88
	v_add_f32_e32 v99, v92, v89
	v_add_f32_e32 v98, v98, v91
	v_add_f32_e32 v99, v99, v93
	v_mul_f32_e32 v98, 0xbfb8aa3b, v98
	v_mul_f32_e32 v99, 0xbfb8aa3b, v99
	v_exp_f32_e32 v98, v98
	v_exp_f32_e32 v99, v99
	v_mov_b32_e32 v103, s8
	v_add_f32_e32 v98, 1.0, v98
	v_add_f32_e32 v99, 1.0, v99
	v_rcp_f32_e32 v98, v98
	v_rcp_f32_e32 v99, v99
	v_max_f32_e32 v103, 0x179abe15, v103
	v_rsq_f32_e32 v103, v103
	v_add_f32_e32 v112, -1.0, v98
	v_add_f32_e32 v113, -1.0, v99
	v_fma_f32 v112, v54, v112, 1.0
	v_fma_f32 v113, v54, v113, 1.0
	v_mul_f32_e32 v112, v51, v112
	v_fmac_f32_e32 v112, v51, v113
	v_mul_f32_e32 v97, v97, v103
	v_mul_f32_e32 v112, v50, v112
	v_mul_f32_e32 v114, v55, v112
	global_store_dword v95, v98, s[18:19]
	global_store_dword v95, v99, s[20:21]
	v_add_f32_dpp v114, v114, v114 quad_perm:[1,0,3,2] row_mask:0xf bank_mask:0xf bound_ctrl:1
	global_store_dword v95, v97, s[22:23]
	s_nop 0
	v_add_f32_dpp v114, v114, v114 quad_perm:[2,3,0,1] row_mask:0xf bank_mask:0xf bound_ctrl:1
	s_nop 1
	v_add_f32_dpp v114, v114, v114 row_half_mirror row_mask:0xf bank_mask:0xf bound_ctrl:1
	v_add_u32_e32 v95, 0x400, v95
	s_addk_i32 s7, 0x200
	v_add_f32_dpp v114, v114, v114 row_mirror row_mask:0xf bank_mask:0xf bound_ctrl:1
	s_nop 1
	v_add_f32_dpp v114, v114, v114 row_bcast:15 row_mask:0xa bank_mask:0xf
	s_nop 1
	v_add_f32_dpp v114, v114, v114 row_bcast:31 row_mask:0xc bank_mask:0xf
	s_nop 1
	v_readlane_b32 s9, v114, 63
	s_and_saveexec_b64 s[4:5], vcc
	v_mov_b32_e32 v103, s9
	v_lshl_add_u64 v[46:47], s[0:1], 4, v[4:5]
	global_store_dword v[46:47], v103, off
	s_or_b64 exec, exec, s[4:5]
	s_add_i32 s6, s6, 1
	s_cmp_lg_u32 s6, 34
	s_cbranch_scc1 .LBB0_710
	s_waitcnt vmcnt(0) lgkmcnt(0)
	s_branch .LBB0_671

.LBB0_1128:
	s_or_b64 exec, exec, s[2:3]
	v_ashrrev_i32_e32 v49, 31, v48
	v_lshlrev_b64 v[54:55], 2, v[48:49]
	v_lshl_add_u64 v[42:43], s[0:1], 0, v[54:55]
	v_mov_b32_e32 v96, v54
	global_load_dword v2, v96, s[0:1]
	global_load_dword v3, v96, s[0:1] offset:1024
	global_load_dword v4, v96, s[0:1] offset:2048
	global_load_dword v5, v96, s[0:1] offset:3072
	v_add_u32_e32 v96, 0x1000, v96
	global_load_dword v6, v96, s[0:1]
	global_load_dword v7, v96, s[0:1] offset:1024
	global_load_dword v8, v96, s[0:1] offset:2048
	global_load_dword v9, v96, s[0:1] offset:3072
	v_add_u32_e32 v96, 0x1000, v96
	global_load_dword v10, v96, s[0:1]
	global_load_dword v11, v96, s[0:1] offset:1024
	global_load_dword v12, v96, s[0:1] offset:2048
	global_load_dword v13, v96, s[0:1] offset:3072
	v_add_u32_e32 v96, 0x1000, v96
	global_load_dword v14, v96, s[0:1]
	global_load_dword v15, v96, s[0:1] offset:1024
	global_load_dword v16, v96, s[0:1] offset:2048
	global_load_dword v17, v96, s[0:1] offset:3072
	v_add_u32_e32 v96, 0x1000, v96
	global_load_dword v18, v96, s[0:1]
	global_load_dword v19, v96, s[0:1] offset:1024
	global_load_dword v20, v96, s[0:1] offset:2048
	global_load_dword v21, v96, s[0:1] offset:3072
	v_add_u32_e32 v96, 0x1000, v96
	global_load_dword v22, v96, s[0:1]
	global_load_dword v23, v96, s[0:1] offset:1024
	global_load_dword v24, v96, s[0:1] offset:2048
	global_load_dword v25, v96, s[0:1] offset:3072
	v_add_u32_e32 v96, 0x1000, v96
	global_load_dword v26, v96, s[0:1]
	global_load_dword v27, v96, s[0:1] offset:1024
	global_load_dword v28, v96, s[0:1] offset:2048
	global_load_dword v29, v96, s[0:1] offset:3072
	v_add_u32_e32 v96, 0x1000, v96
	global_load_dword v30, v96, s[0:1]
	global_load_dword v31, v96, s[0:1] offset:1024
	global_load_dword v32, v96, s[0:1] offset:2048
	global_load_dword v33, v96, s[0:1] offset:3072
	v_add_u32_e32 v96, 0x1000, v96
	global_load_dword v34, v96, s[0:1]
	global_load_dword v35, v96, s[0:1] offset:1024
	global_load_dword v36, v96, s[0:1] offset:2048
	global_load_dword v37, v96, s[0:1] offset:3072
	v_add_u32_e32 v96, 0x1000, v96
	global_load_dword v38, v96, s[0:1]
	global_load_dword v39, v96, s[0:1] offset:1024
	global_load_dword v40, v96, s[0:1] offset:2048
	global_load_dword v41, v96, s[0:1] offset:3072
	v_add_u32_e32 v96, 0x1000, v96
	global_load_dword v58, v96, s[0:1]
	global_load_dword v59, v96, s[0:1] offset:1024
	global_load_dword v60, v96, s[0:1] offset:2048
	global_load_dword v61, v96, s[0:1] offset:3072
	v_add_u32_e32 v96, 0x1000, v96
	global_load_dword v62, v96, s[0:1]
	global_load_dword v63, v96, s[0:1] offset:1024
	global_load_dword v64, v96, s[0:1] offset:2048
	global_load_dword v65, v96, s[0:1] offset:3072
	v_add_u32_e32 v96, 0x1000, v96
	global_load_dword v66, v96, s[0:1]
	global_load_dword v67, v96, s[0:1] offset:1024
	global_load_dword v68, v96, s[0:1] offset:2048
	global_load_dword v69, v96, s[0:1] offset:3072
	v_add_u32_e32 v96, 0x1000, v96
	global_load_dword v70, v96, s[0:1]
	global_load_dword v71, v96, s[0:1] offset:1024
	global_load_dword v72, v96, s[0:1] offset:2048
	global_load_dword v73, v96, s[0:1] offset:3072
	v_add_u32_e32 v96, 0x1000, v96
	global_load_dword v74, v96, s[0:1]
	global_load_dword v75, v96, s[0:1] offset:1024
	global_load_dword v76, v96, s[0:1] offset:2048
	global_load_dword v77, v96, s[0:1] offset:3072
	v_add_u32_e32 v96, 0x1000, v96
	global_load_dword v78, v96, s[0:1]
	global_load_dword v79, v96, s[0:1] offset:1024
	global_load_dword v80, v96, s[0:1] offset:2048
	global_load_dword v81, v96, s[0:1] offset:3072
	s_movk_i32 s2, 0x1000
	s_movk_i32 s3, 0x2000
	s_movk_i32 s2, 0x3000
	s_nop 0
	s_mov_b32 s4, 0xb000
	s_nop 0
	s_movk_i32 s2, 0x5000
	s_nop 0
	v_readlane_b32 s44, v210, 34
	s_nop 0
	s_movk_i32 s2, 0x6000
	s_nop 0
	s_movk_i32 s2, 0x7000
	s_nop 0
	s_mov_b32 s2, 0x8000
	s_nop 0
	s_mov_b32 s2, 0x9000
	s_nop 0
	s_mov_b32 s2, 0xa000
	s_nop 0
	s_mov_b32 s2, 0xc000
	s_nop 0
	s_nop 0
	s_nop 0
	s_mov_b32 s2, 0xd000
	s_nop 0
	s_mov_b32 s2, 0xe000
	s_nop 0
	s_mov_b32 s2, 0xf000
	s_nop 0
	s_nop 0
	s_nop 0
	s_nop 0
	s_nop 0
	s_nop 0
	s_nop 0
	s_nop 0
	s_nop 0
	s_nop 0
	s_nop 0
	s_nop 0
	s_nop 0
	v_add_u32_e32 v46, s7, v48
	v_ashrrev_i32_e32 v47, 31, v46
	v_lshlrev_b64 v[46:47], 2, v[46:47]
	v_readlane_b32 s48, v210, 38
	v_readlane_b32 s49, v210, 39
	v_readlane_b32 s50, v210, 40
	v_readlane_b32 s51, v210, 41
	v_lshl_add_u64 v[50:51], s[48:49], 0, v[46:47]
	global_load_dword v82, v[50:51], off
	v_lshl_add_u64 v[46:47], s[50:51], 0, v[46:47]
	global_load_dword v83, v[46:47], off
	v_readlane_b32 s45, v210, 35
	v_readlane_b32 s46, v210, 36
	v_readlane_b32 s47, v210, 37
	v_readlane_b32 s52, v210, 42
	v_readlane_b32 s53, v210, 43
	v_readlane_b32 s54, v210, 44
	v_readlane_b32 s55, v210, 45
	v_readlane_b32 s56, v210, 46
	v_readlane_b32 s57, v210, 47
	v_readlane_b32 s58, v210, 48
	v_readlane_b32 s59, v210, 49
	s_ashr_i32 s35, s34, 31
	v_readlane_b32 s44, v210, 50
	s_lshl_b64 s[2:3], s[34:35], 11
	s_lshl_b64 s[36:37], s[34:35], 4
	s_lshl_b64 s[38:39], s[34:35], 10
	v_readlane_b32 s46, v210, 52
	v_readlane_b32 s47, v210, 53
	s_add_u32 s2, s46, s2
	s_addc_u32 s3, s47, s3
	s_mul_i32 s9, s34, 0xf00
	v_ashrrev_i32_e32 v52, 6, v48
	v_lshl_add_u64 v[48:49], v[48:49], 1, s[2:3]
	v_readlane_b32 s2, v208, 22
	s_mul_hi_i32 s5, s34, 0xf00
	s_add_u32 s2, s2, s9
	s_addc_u32 s3, s69, s5
	v_lshl_add_u64 v[50:51], s[2:3], 0, v[54:55]
	s_add_u32 s2, s24, s36
	v_ashrrev_i32_e32 v53, 31, v52
	v_readlane_b32 s45, v210, 51
	s_addc_u32 s3, s25, s37
	v_lshl_add_u64 v[56:57], s[38:39], 0, v[54:55]
	s_mov_b32 s4, 0
	v_lshl_add_u64 v[52:53], v[52:53], 2, s[2:3]
	v_lshl_add_u64 v[54:55], s[26:27], 0, v[56:57]
	v_lshl_add_u64 v[56:57], s[44:45], 0, v[56:57]
	s_mov_b64 s[2:3], 0
	s_waitcnt lgkmcnt(0)
	s_barrier
	v_readlane_b32 s48, v210, 54
	v_readlane_b32 s49, v210, 55
	v_readlane_b32 s50, v210, 56
	v_readlane_b32 s51, v210, 57
	v_readlane_b32 s52, v210, 58
	v_readlane_b32 s53, v210, 59
	v_readlane_b32 s54, v210, 60
	v_readlane_b32 s55, v210, 61
	v_readlane_b32 s56, v210, 62
	v_readlane_b32 s57, v210, 63
	v_readlane_b32 s58, v209, 0
	v_readlane_b32 s59, v209, 1
	s_mov_b64 s[36:37], 0xf00
	s_mov_b64 s[38:39], 0x800
	v_mov_b32_e32 v94, 0
	ds_read_b128 v[136:139], v94 offset:0
	ds_read_b128 v[140:143], v94 offset:16
	ds_read_b128 v[144:147], v94 offset:32
	ds_read_b128 v[148:151], v94 offset:48
	ds_read_b128 v[152:155], v94 offset:64
	ds_read_b128 v[156:159], v94 offset:80
	ds_read_b128 v[160:163], v94 offset:96
	ds_read_b128 v[164:167], v94 offset:112
	ds_read_b128 v[184:187], v94 offset:128
	ds_read_b128 v[188:191], v94 offset:144
	ds_read_b128 v[192:195], v94 offset:160
	ds_read_b128 v[196:199], v94 offset:176
	ds_read_b128 v[200:203], v94 offset:192
	ds_read_b128 v[212:215], v94 offset:208
	ds_read_b128 v[216:219], v94 offset:224
	ds_read_b128 v[220:223], v94 offset:240
	v_lshl_add_u64 v[96:97], v[54:55], 0, s[2:3]
	global_load_dword v84, v[96:97], off
	v_lshl_add_u64 v[96:97], v[56:57], 0, s[2:3]
	global_load_dword v85, v[96:97], off
	global_load_dword v86, v[52:53], off
	global_load_dword v87, v[50:51], off
	s_add_u32 s2, s2, 0x400
	s_addc_u32 s3, s3, 0
	v_lshl_add_u64 v[52:53], v[52:53], 0, 16
	v_lshl_add_u64 v[50:51], v[50:51], 0, s[36:37]
	v_lshl_add_u64 v[96:97], v[54:55], 0, s[2:3]
	global_load_dword v100, v[96:97], off
	v_lshl_add_u64 v[96:97], v[56:57], 0, s[2:3]
	global_load_dword v101, v[96:97], off
	global_load_dword v102, v[52:53], off
	global_load_dword v103, v[50:51], off
	s_add_u32 s2, s2, 0x400
	s_addc_u32 s3, s3, 0
	v_lshl_add_u64 v[52:53], v[52:53], 0, 16
	v_lshl_add_u64 v[50:51], v[50:51], 0, s[36:37]
	s_waitcnt vmcnt(4)
	s_branch .Lro_even_entry
.LBB0_1129:
	s_waitcnt vmcnt(5)
.Lro_even_entry:
	v_mov_b32_e32 v94, s4
	v_add_f32_e32 v88, v84, v85
	v_mul_f32_e32 v91, v86, v87
	v_mov_b32_e32 v89, v88
	v_lshl_add_u64 v[96:97], v[54:55], 0, s[2:3]
	global_load_dword v84, v[96:97], off
	v_lshl_add_u64 v[96:97], v[56:57], 0, s[2:3]
	global_load_dword v85, v[96:97], off
	global_load_dword v86, v[52:53], off
	global_load_dword v87, v[50:51], off
	s_add_u32 s2, s2, 0x400
	s_addc_u32 s3, s3, 0
	v_lshl_add_u64 v[52:53], v[52:53], 0, 16
	v_lshl_add_u64 v[50:51], v[50:51], 0, s[36:37]
	s_waitcnt lgkmcnt(12)
	v_pk_mul_f32 v[92:93], v[136:137], v[2:3]
	v_pk_fma_f32 v[92:93], v[138:139], v[4:5], v[92:93]
	ds_read_b128 v[136:139], v94 offset:256
	v_add_f32_dpp v89, v89, v89 quad_perm:[1,0,3,2] row_mask:0xf bank_mask:0xf bound_ctrl:1
	v_pk_fma_f32 v[92:93], v[140:141], v[6:7], v[92:93]
	v_pk_fma_f32 v[92:93], v[142:143], v[8:9], v[92:93]
	ds_read_b128 v[140:143], v94 offset:272
	v_add_f32_dpp v89, v89, v89 quad_perm:[2,3,0,1] row_mask:0xf bank_mask:0xf bound_ctrl:1
	v_pk_fma_f32 v[92:93], v[144:145], v[10:11], v[92:93]
	v_pk_fma_f32 v[92:93], v[146:147], v[12:13], v[92:93]
	ds_read_b128 v[144:147], v94 offset:288
	v_add_f32_dpp v89, v89, v89 row_half_mirror row_mask:0xf bank_mask:0xf bound_ctrl:1
	v_pk_fma_f32 v[92:93], v[148:149], v[14:15], v[92:93]
	v_pk_fma_f32 v[92:93], v[150:151], v[16:17], v[92:93]
	ds_read_b128 v[148:151], v94 offset:304
	v_add_f32_dpp v89, v89, v89 row_mirror row_mask:0xf bank_mask:0xf bound_ctrl:1
	s_waitcnt lgkmcnt(12)
	v_pk_fma_f32 v[92:93], v[152:153], v[18:19], v[92:93]
	v_pk_fma_f32 v[92:93], v[154:155], v[20:21], v[92:93]
	ds_read_b128 v[152:155], v94 offset:320
	v_add_f32_dpp v89, v89, v89 row_bcast:15 row_mask:0xa bank_mask:0xf
	v_pk_fma_f32 v[92:93], v[156:157], v[22:23], v[92:93]
	v_pk_fma_f32 v[92:93], v[158:159], v[24:25], v[92:93]
	ds_read_b128 v[156:159], v94 offset:336
	v_add_f32_dpp v89, v89, v89 row_bcast:31 row_mask:0xc bank_mask:0xf
	v_pk_fma_f32 v[92:93], v[160:161], v[26:27], v[92:93]
	v_pk_fma_f32 v[92:93], v[162:163], v[28:29], v[92:93]
	ds_read_b128 v[160:163], v94 offset:352
	v_readlane_b32 s5, v89, 63
	v_pk_fma_f32 v[92:93], v[164:165], v[30:31], v[92:93]
	v_pk_fma_f32 v[92:93], v[166:167], v[32:33], v[92:93]
	ds_read_b128 v[164:167], v94 offset:368
	v_mov_b32_e32 v89, s5
	v_fmac_f32_e32 v88, 0xbc800000, v89
	s_waitcnt lgkmcnt(12)
	v_pk_fma_f32 v[92:93], v[184:185], v[34:35], v[92:93]
	v_pk_fma_f32 v[92:93], v[186:187], v[36:37], v[92:93]
	ds_read_b128 v[184:187], v94 offset:384
	v_mul_f32_e32 v90, v88, v88
	v_pk_fma_f32 v[92:93], v[188:189], v[38:39], v[92:93]
	v_pk_fma_f32 v[92:93], v[190:191], v[40:41], v[92:93]
	ds_read_b128 v[188:191], v94 offset:400
	v_add_f32_dpp v90, v90, v90 quad_perm:[1,0,3,2] row_mask:0xf bank_mask:0xf bound_ctrl:1
	v_pk_fma_f32 v[92:93], v[192:193], v[58:59], v[92:93]
	v_pk_fma_f32 v[92:93], v[194:195], v[60:61], v[92:93]
	ds_read_b128 v[192:195], v94 offset:416
	v_add_f32_dpp v90, v90, v90 quad_perm:[2,3,0,1] row_mask:0xf bank_mask:0xf bound_ctrl:1
	v_pk_fma_f32 v[92:93], v[196:197], v[62:63], v[92:93]
	v_pk_fma_f32 v[92:93], v[198:199], v[64:65], v[92:93]
	ds_read_b128 v[196:199], v94 offset:432
	v_add_f32_dpp v90, v90, v90 row_half_mirror row_mask:0xf bank_mask:0xf bound_ctrl:1
	s_waitcnt lgkmcnt(12)
	v_pk_fma_f32 v[92:93], v[200:201], v[66:67], v[92:93]
	v_pk_fma_f32 v[92:93], v[202:203], v[68:69], v[92:93]
	ds_read_b128 v[200:203], v94 offset:448
	v_add_f32_dpp v90, v90, v90 row_mirror row_mask:0xf bank_mask:0xf bound_ctrl:1
	v_pk_fma_f32 v[92:93], v[212:213], v[70:71], v[92:93]
	v_pk_fma_f32 v[92:93], v[214:215], v[72:73], v[92:93]
	ds_read_b128 v[212:215], v94 offset:464
	v_add_f32_dpp v90, v90, v90 row_bcast:15 row_mask:0xa bank_mask:0xf
	v_pk_fma_f32 v[92:93], v[216:217], v[74:75], v[92:93]
	v_pk_fma_f32 v[92:93], v[218:219], v[76:77], v[92:93]
	ds_read_b128 v[216:219], v94 offset:480
	v_add_f32_dpp v90, v90, v90 row_bcast:31 row_mask:0xc bank_mask:0xf
	v_pk_fma_f32 v[92:93], v[220:221], v[78:79], v[92:93]
	v_pk_fma_f32 v[92:93], v[222:223], v[80:81], v[92:93]
	ds_read_b128 v[220:223], v94 offset:496
	s_nop 1
	v_readlane_b32 s5, v90, 63
	v_add_f32_e32 v94, v92, v93
	v_mov_b32_e32 v95, s5
	v_fmamk_f32 v95, v95, 0x3c800000, v176
	v_rsq_f32_e32 v95, v95
	v_mul_f32_e32 v88, v88, v82
	s_addk_i32 s4, 0x100
	v_fma_f32 v88, v88, v95, v83
	v_add_f32_e32 v88, v88, v91
	v_mul_f32_e32 v88, v88, v94
	v_cvt_pk_bf16_f32 v88, v88, s0
	global_store_short v[48:49], v88, off
	v_lshl_add_u64 v[48:49], v[48:49], 0, s[38:39]
	s_waitcnt vmcnt(5)
	v_mov_b32_e32 v94, s4
	v_add_f32_e32 v88, v100, v101
	v_mul_f32_e32 v91, v102, v103
	v_mov_b32_e32 v89, v88
	v_lshl_add_u64 v[96:97], v[54:55], 0, s[2:3]
	global_load_dword v100, v[96:97], off
	v_lshl_add_u64 v[96:97], v[56:57], 0, s[2:3]
	global_load_dword v101, v[96:97], off
	global_load_dword v102, v[52:53], off
	global_load_dword v103, v[50:51], off
	s_add_u32 s2, s2, 0x400
	s_addc_u32 s3, s3, 0
	v_lshl_add_u64 v[52:53], v[52:53], 0, 16
	v_lshl_add_u64 v[50:51], v[50:51], 0, s[36:37]
	s_waitcnt lgkmcnt(12)
	v_pk_mul_f32 v[92:93], v[136:137], v[2:3]
	v_pk_fma_f32 v[92:93], v[138:139], v[4:5], v[92:93]
	ds_read_b128 v[136:139], v94 offset:256
	v_add_f32_dpp v89, v89, v89 quad_perm:[1,0,3,2] row_mask:0xf bank_mask:0xf bound_ctrl:1
	v_pk_fma_f32 v[92:93], v[140:141], v[6:7], v[92:93]
	v_pk_fma_f32 v[92:93], v[142:143], v[8:9], v[92:93]
	ds_read_b128 v[140:143], v94 offset:272
	v_add_f32_dpp v89, v89, v89 quad_perm:[2,3,0,1] row_mask:0xf bank_mask:0xf bound_ctrl:1
	v_pk_fma_f32 v[92:93], v[144:145], v[10:11], v[92:93]
	v_pk_fma_f32 v[92:93], v[146:147], v[12:13], v[92:93]
	ds_read_b128 v[144:147], v94 offset:288
	v_add_f32_dpp v89, v89, v89 row_half_mirror row_mask:0xf bank_mask:0xf bound_ctrl:1
	v_pk_fma_f32 v[92:93], v[148:149], v[14:15], v[92:93]
	v_pk_fma_f32 v[92:93], v[150:151], v[16:17], v[92:93]
	ds_read_b128 v[148:151], v94 offset:304
	v_add_f32_dpp v89, v89, v89 row_mirror row_mask:0xf bank_mask:0xf bound_ctrl:1
	s_waitcnt lgkmcnt(12)
	v_pk_fma_f32 v[92:93], v[152:153], v[18:19], v[92:93]
	v_pk_fma_f32 v[92:93], v[154:155], v[20:21], v[92:93]
	ds_read_b128 v[152:155], v94 offset:320
	v_add_f32_dpp v89, v89, v89 row_bcast:15 row_mask:0xa bank_mask:0xf
	v_pk_fma_f32 v[92:93], v[156:157], v[22:23], v[92:93]
	v_pk_fma_f32 v[92:93], v[158:159], v[24:25], v[92:93]
	ds_read_b128 v[156:159], v94 offset:336
	v_add_f32_dpp v89, v89, v89 row_bcast:31 row_mask:0xc bank_mask:0xf
	v_pk_fma_f32 v[92:93], v[160:161], v[26:27], v[92:93]
	v_pk_fma_f32 v[92:93], v[162:163], v[28:29], v[92:93]
	ds_read_b128 v[160:163], v94 offset:352
	v_readlane_b32 s5, v89, 63
	v_pk_fma_f32 v[92:93], v[164:165], v[30:31], v[92:93]
	v_pk_fma_f32 v[92:93], v[166:167], v[32:33], v[92:93]
	ds_read_b128 v[164:167], v94 offset:368
	v_mov_b32_e32 v89, s5
	v_fmac_f32_e32 v88, 0xbc800000, v89
	s_waitcnt lgkmcnt(12)
	v_pk_fma_f32 v[92:93], v[184:185], v[34:35], v[92:93]
	v_pk_fma_f32 v[92:93], v[186:187], v[36:37], v[92:93]
	ds_read_b128 v[184:187], v94 offset:384
	v_mul_f32_e32 v90, v88, v88
	v_pk_fma_f32 v[92:93], v[188:189], v[38:39], v[92:93]
	v_pk_fma_f32 v[92:93], v[190:191], v[40:41], v[92:93]
	ds_read_b128 v[188:191], v94 offset:400
	v_add_f32_dpp v90, v90, v90 quad_perm:[1,0,3,2] row_mask:0xf bank_mask:0xf bound_ctrl:1
	v_pk_fma_f32 v[92:93], v[192:193], v[58:59], v[92:93]
	v_pk_fma_f32 v[92:93], v[194:195], v[60:61], v[92:93]
	ds_read_b128 v[192:195], v94 offset:416
	v_add_f32_dpp v90, v90, v90 quad_perm:[2,3,0,1] row_mask:0xf bank_mask:0xf bound_ctrl:1
	v_pk_fma_f32 v[92:93], v[196:197], v[62:63], v[92:93]
	v_pk_fma_f32 v[92:93], v[198:199], v[64:65], v[92:93]
	ds_read_b128 v[196:199], v94 offset:432
	v_add_f32_dpp v90, v90, v90 row_half_mirror row_mask:0xf bank_mask:0xf bound_ctrl:1
	s_waitcnt lgkmcnt(12)
	v_pk_fma_f32 v[92:93], v[200:201], v[66:67], v[92:93]
	v_pk_fma_f32 v[92:93], v[202:203], v[68:69], v[92:93]
	ds_read_b128 v[200:203], v94 offset:448
	v_add_f32_dpp v90, v90, v90 row_mirror row_mask:0xf bank_mask:0xf bound_ctrl:1
	v_pk_fma_f32 v[92:93], v[212:213], v[70:71], v[92:93]
	v_pk_fma_f32 v[92:93], v[214:215], v[72:73], v[92:93]
	ds_read_b128 v[212:215], v94 offset:464
	v_add_f32_dpp v90, v90, v90 row_bcast:15 row_mask:0xa bank_mask:0xf
	v_pk_fma_f32 v[92:93], v[216:217], v[74:75], v[92:93]
	v_pk_fma_f32 v[92:93], v[218:219], v[76:77], v[92:93]
	ds_read_b128 v[216:219], v94 offset:480
	v_add_f32_dpp v90, v90, v90 row_bcast:31 row_mask:0xc bank_mask:0xf
	v_pk_fma_f32 v[92:93], v[220:221], v[78:79], v[92:93]
	v_pk_fma_f32 v[92:93], v[222:223], v[80:81], v[92:93]
	ds_read_b128 v[220:223], v94 offset:496
	s_nop 1
	v_readlane_b32 s5, v90, 63
	v_add_f32_e32 v94, v92, v93
	v_mov_b32_e32 v95, s5
	v_fmamk_f32 v95, v95, 0x3c800000, v176
	v_rsq_f32_e32 v95, v95
	v_mul_f32_e32 v88, v88, v82
	s_addk_i32 s4, 0x100
	v_fma_f32 v88, v88, v95, v83
	v_add_f32_e32 v88, v88, v91
	v_mul_f32_e32 v88, v88, v94
	v_cvt_pk_bf16_f32 v88, v88, s0
	global_store_short v[48:49], v88, off
	v_lshl_add_u64 v[48:49], v[48:49], 0, s[38:39]
	s_cmpk_eq_i32 s4, 0x2200
	s_cbranch_scc0 .LBB0_1129
	s_waitcnt vmcnt(0) lgkmcnt(0)
	s_mov_b32 s2, 0x8800
	s_mov_b32 s3, 0
	v_readlane_b32 s2, v208, 21
	s_add_i32 s8, s8, s66
	s_add_i32 s34, s34, s2
	s_cmp_lt_i32 s8, s6
	s_barrier
	s_cbranch_scc1 .LBB0_1125
	v_readlane_b32 s42, v208, 51
	v_readlane_b32 s54, v209, 14
	v_readlane_b32 s43, v208, 52
	v_readlane_b32 s55, v209, 15
	s_mov_b32 s56, 0x10000
	s_mov_b32 s57, 0x20000
	s_mov_b32 s58, 0x30000
	s_movk_i32 s59, 0x70
	s_movk_i32 s53, 0x2000
	s_mov_b32 s52, 0xb000
